# stack: P6 XCD-alternating GEMM order + FoX loop rotation (next-tile loads before barrier) + barrier followers poll global generation + w_down transposes moved into phase-2 tail
# speedup vs baseline: 1.0087x; 1.0087x over previous
; __global__ void __launch_bounds__(512, 2) fwd_mega(Params P) {
;     ...
;     xcd_barrier(xbar, wid_s);
;     { EpiUp E{(bf16_t*)(ws + OFF_FFB)}; run_gemm(glds, (const bf16_t*)(ws + OFF_H1B), (const bf16_t*)(ws + OFF_WUP), 4096, DM, E, wid_s); }
.LBB0_806:
	s_or_b64 exec, exec, s[0:1]
	s_mov_b32 s98, 0
